# foxmov: FoX O accumulator kept in v[2:33] across the 3x unrolled step loop (32 v_mov_b64 copies per 3 steps removed; copies only on loop entry/exit), on v11
# speedup vs baseline: 1.0023x; 1.0013x over previous
; __device__ __forceinline__ float bf2f(short s) { return __uint_as_float(((unsigned)(unsigned short)s) << 16); }
; #define LOADT(i, kreg, vreg, creg) do { const int k0_ = KEY0(i); kreg = *(const u32x4*)(A.K + (size_t)(k0_ + lane) * A.ldkv + wid * 8); vreg = *(const u32x4*)(A.V + (size_t)(k0_ + lane) * A.ldkv + wid * 8); \
;         if (MODE == M_FOX) { if (tid < 64) creg = A.cf[k0_ + tid] * LOG2E; } } while (0)
; template <int MODE>
; __device__ __forceinline__ void attn_unit(LAS unsigned char* lds, const AttnArgs& A, int qb) {
;     ...
;     float qb2 = 0.f, cq2 = 0.f;
;     if (MODE == M_FOX) {
;         float s = 0.f;
; #pragma unroll
;         for (int d0 = 0; d0 < 4; ++d0)
; #pragma unroll
;             for (int e = 0; e < 8; ++e) { const float x = bf2f(qr[d0][e]); s += x * x; }
;         s += __shfl_xor(s, 32);
;         qb2 = sqrtf(s * A.kmax2) * C2 * 1.01f;
;         cq2 = A.cf[row] * LOG2E;
;     }
;     const int NT = (MODE == M_XA || MODE == M_MOBA) ? 4 : (q0 / 64 + 4);
;     f32x16 o0, o1;
; #pragma unroll
;     for (int r = 0; r < 16; ++r) { o0[r] = 0.f; o1[r] = 0.f; }
;     float m_run = -1e30f, l_run = 0.f, T = 0.f;
;     u32x4 k1 = (u32x4){0u, 0u, 0u, 0u}, v1 = k1, k2 = k1, v2 = k1, k3 = k1, v3 = k1; float c1 = 0.f, c2 = 0.f, c3 = 0.f;
;     ...
;     LOADT(0, k1, v1, c1); if (NT > 1) LOADT(1, k2, v2, c2); if (NT > 2) LOADT(2, k3, v3, c3);
;     STORET(0, k1, v1, c1);
;     __syncthreads();
;     const int kperm = (r32 & ~15) | (r32 & 3) | ((r32 & 4) << 1) | ((r32 & 8) >> 1);
;     bool prev_active = false; int prevbuf = 0; bf16x8 pkP0 = (bf16x8){0, 0, 0, 0, 0, 0, 0, 0}, pkP1 = pkP0, pkP2 = pkP0, pkP3 = pkP0;
.LBB0_960:
	s_or_b64 exec, exec, s[4:5]
	s_lshl_b32 s2, s42, 10
	s_add_i32 s46, s2, 0
	v_lshlrev_b32_e32 v179, 4, v6
	s_lshl_b32 s3, s42, 7
	v_add_u32_e32 v180, s46, v179
	s_add_i32 s46, s46, s3
	v_lshlrev_b32_e32 v181, 1, v6
	v_add_u32_e32 v182, s46, v181
	v_lshl_add_u32 v183, v2, 2, 0
	s_waitcnt vmcnt(5)
	ds_write_b128 v180, v[114:117]
	s_waitcnt vmcnt(4)
	ds_write_b16 v182, v118 offset:8192
	ds_write_b16_d16_hi v182, v118 offset:8336
	ds_write_b16 v182, v119 offset:8480
	ds_write_b16_d16_hi v182, v119 offset:8624
	ds_write_b16 v182, v120 offset:8768
	ds_write_b16_d16_hi v182, v120 offset:8912
	ds_write_b16 v182, v121 offset:9056
	ds_write_b16_d16_hi v182, v121 offset:9200
	s_and_saveexec_b64 s[4:5], s[6:7]
	ds_write_b32 v183, v157 offset:17408
	s_or_b64 exec, exec, s[4:5]
	s_waitcnt lgkmcnt(9)
	v_add_f32_e32 v4, v10, v12
	v_mul_f32_e32 v4, v9, v4
	s_mov_b32 s2, 0xf800000
	v_mul_f32_e32 v5, 0x4f800000, v4
	v_cmp_gt_f32_e32 vcc, s2, v4
	s_mul_i32 s4, s42, 0xfffffb84
	s_add_i32 s46, s46, s4
	v_cndmask_b32_e32 v4, v4, v5, vcc
	v_sqrt_f32_e32 v5, v4
	s_mov_b32 s4, 0x3fb8aa3b
	v_mul_f32_e32 v184, 0x3fb8aa3b, v11
	s_lshl_b32 s44, s0, 2
	v_add_u32_e32 v9, -1, v5
	v_fma_f32 v10, -v9, v5, v4
	v_cmp_ge_f32_e64 s[8:9], 0, v10
	v_add_u32_e32 v10, 1, v5
	s_add_i32 s45, s44, 4
	v_cndmask_b32_e64 v9, v5, v9, s[8:9]
	v_fma_f32 v5, -v10, v5, v4
	v_cmp_lt_f32_e64 s[8:9], 0, v5
	s_or_b32 s47, s44, 2
	s_or_b32 s48, s43, 31
	v_cndmask_b32_e64 v5, v9, v10, s[8:9]
	v_mul_f32_e32 v9, 0x37800000, v5
	v_cndmask_b32_e32 v5, v5, v9, vcc
	v_mov_b32_e32 v9, 0x260
	v_cmp_class_f32_e32 vcc, v4, v9
	s_add_i32 s52, s80, 0xff
	s_lshl_b32 s0, s0, 10
	v_cndmask_b32_e32 v4, v5, v4, vcc
	v_mul_f32_e32 v4, 0x3e38aa3b, v4
	v_mul_f32_e32 v5, 0x3f8147ae, v4
	v_min_f32_e32 v189, 0x42400000, v5
	v_fma_f32 v160, v11, s4, -v189
	s_mul_i32 s4, s42, 0x3fc
	s_add_i32 s49, s46, s4
	s_add_i32 s50, s49, s3
	s_sub_i32 s3, s80, 64
	v_fmamk_f32 v190, v4, 0x3f8147ae, v184
	v_add_u32_e32 v4, s3, v6
	v_ashrrev_i32_e32 v5, 31, v4
	v_lshlrev_b64 v[4:5], 11, v[4:5]
	v_lshl_add_u64 v[4:5], v[4:5], 0, s[10:11]
	s_add_i32 s3, s80, 0xffffff80
	v_lshl_add_u64 v[162:163], s[14:15], 0, v[4:5]
	v_lshl_add_u64 v[164:165], s[16:17], 0, v[4:5]
	v_add_u32_e32 v4, s3, v6
	s_add_u32 s1, s40, s1
	v_lshlrev_b32_e32 v10, 1, v2
	v_lshrrev_b32_e32 v12, 1, v2
	v_ashrrev_i32_e32 v5, 31, v4
	s_addc_u32 s3, s41, 0
	v_lshlrev_b32_e32 v156, 3, v7
	v_and_b32_e32 v9, 19, v2
	v_and_b32_e32 v10, 8, v10
	v_and_b32_e32 v12, 4, v12
	v_lshlrev_b32_e32 v187, 10, v7
	v_cmp_eq_u32_e64 s[8:9], 0, v6
	v_lshlrev_b64 v[4:5], 11, v[4:5]
	v_add_lshl_u32 v6, s80, v6, 11
	v_mov_b32_e32 v7, v1
	s_add_u32 s0, s1, s0
	v_mov_b32_e32 v80, v1
	v_mov_b32_e32 v81, v1
	v_mov_b32_e32 v140, v1
	v_mov_b32_e32 v141, v1
	v_or3_b32 v9, v10, v9, v12
	v_mul_u32_u24_e32 v185, 0x90, v8
	v_lshl_add_u64 v[4:5], v[4:5], 0, s[10:11]
	v_lshl_add_u64 v[6:7], v[6:7], 0, s[10:11]
	s_addc_u32 s1, s3, 0
	v_mov_b32_e32 v66, v1
	v_mov_b32_e32 v67, v1
	v_mov_b32_e32 v68, v1
	v_mov_b32_e32 v69, v1
	v_mov_b32_e32 v70, v1
	v_mov_b32_e32 v71, v1
	v_mov_b32_e32 v72, v1
	v_mov_b32_e32 v73, v1
	v_mov_b32_e32 v74, v1
	v_mov_b32_e32 v75, v1
	v_mov_b32_e32 v76, v1
	v_mov_b32_e32 v77, v1
	v_mov_b32_e32 v78, v1
	v_mov_b32_e32 v79, v1
	v_mov_b32_e32 v138, v1
	v_mov_b32_e32 v139, v1
	v_mov_b64_e32 v[148:149], v[140:141]
	v_mov_b64_e32 v[144:145], v[140:141]
	v_mov_b64_e32 v[152:153], v[140:141]
	v_mov_b64_e32 v[96:97], v[80:81]
	v_lshlrev_b64 v[158:159], 10, v[154:155]
	s_mov_b32 s2, 0
	s_mov_b32 s51, 8
	v_lshl_add_u32 v186, v9, 4, 0
	v_lshl_add_u32 v188, v156, 2, 0
	v_mov_b32_e32 v161, v160
	v_add3_u32 v191, 0, v185, v0
	v_lshl_add_u64 v[166:167], s[16:17], 0, v[4:5]
	v_lshl_add_u64 v[168:169], s[14:15], 0, v[6:7]
	v_lshl_add_u64 v[170:171], s[16:17], 0, v[6:7]
	v_lshl_add_u64 v[172:173], v[2:3], 2, s[0:1]
	v_lshl_add_u64 v[174:175], s[14:15], 0, v[4:5]
	v_mov_b32_e32 v193, 0xf149f2ca
	v_mov_b32_e32 v155, 0
	s_mov_b64 s[4:5], 0
	s_mov_b32 s53, 5
	v_mov_b64_e32 v[146:147], v[138:139]
	v_mov_b64_e32 v[142:143], v[138:139]
	v_mov_b64_e32 v[150:151], v[138:139]
	v_mov_b64_e32 v[94:95], v[78:79]
	v_mov_b64_e32 v[92:93], v[76:77]
	v_mov_b64_e32 v[90:91], v[74:75]
	v_mov_b64_e32 v[88:89], v[72:73]
	v_mov_b64_e32 v[86:87], v[70:71]
	v_mov_b64_e32 v[84:85], v[68:69]
	v_mov_b64_e32 v[82:83], v[66:67]
	v_mov_b64_e32 v[2:3], v[66:67]
	v_mov_b64_e32 v[4:5], v[66:67]
	v_mov_b64_e32 v[6:7], v[66:67]
	v_mov_b64_e32 v[8:9], v[66:67]
	v_mov_b64_e32 v[10:11], v[66:67]
	v_mov_b64_e32 v[12:13], v[66:67]
	v_mov_b64_e32 v[14:15], v[66:67]
	v_mov_b64_e32 v[16:17], v[66:67]
	v_mov_b64_e32 v[18:19], v[66:67]
	v_mov_b64_e32 v[20:21], v[66:67]
	v_mov_b64_e32 v[22:23], v[66:67]
	v_mov_b64_e32 v[24:25], v[66:67]
	v_mov_b64_e32 v[26:27], v[66:67]
	v_mov_b64_e32 v[28:29], v[66:67]
	v_mov_b64_e32 v[30:31], v[66:67]
	v_mov_b64_e32 v[32:33], v[66:67]
	s_waitcnt lgkmcnt(0)
	s_barrier
	s_branch .LBB0_964

; #define LOADT(i, kreg, vreg, creg) do { const int k0_ = KEY0(i); kreg = *(const u32x4*)(A.K + (size_t)(k0_ + lane) * A.ldkv + wid * 8); vreg = *(const u32x4*)(A.V + (size_t)(k0_ + lane) * A.ldkv + wid * 8); \
;         if (MODE == M_FOX) { if (tid < 64) creg = A.cf[k0_ + tid] * LOG2E; } } while (0)
; template <int MODE>
; __device__ __forceinline__ void attn_unit(LAS unsigned char* lds, const AttnArgs& A, int qb) {
;     ...
;     for (int i0 = 0; i0 < NT; i0 += 3) {
;         { const int i = i0 + 0; if (i >= NT) break;
;         const int key0 = KEY0(i);
;         if (i + 3 < NT) LOADT(i + 3, k1, v1, c1);
.LBB0_964:
	s_add_i32 s55, s53, -5
	s_cmp_ge_u32 s55, s45
	s_mov_b64 s[10:11], -1
	s_cbranch_scc1 .LBB0_963
	s_add_i32 s0, s53, -2
	s_cmp_lt_u32 s0, s45
	s_cselect_b64 s[24:25], -1, 0
	s_cmp_ge_u32 s0, s45
	v_lshl_add_u64 v[230:231], v[168:169], 0, s[20:21]
	global_load_dwordx4 v[114:117], v[230:231], off
	v_lshl_add_u64 v[230:231], v[170:171], 0, s[20:21]
	global_load_dwordx4 v[118:121], v[230:231], off
	s_and_saveexec_b64 s[10:11], s[6:7]
	s_cbranch_execz .LBB0_968
	global_load_dword v157, v[172:173], off offset:256

; #define LAS __attribute__((address_space(3)))
; #define PVS(s, pk) do { const bf16x8 a0_ = *(const LAS bf16x8*)(vb + (s) * 32), a1_ = *(const LAS bf16x8*)(vb + 32 * VT_STRIDE + (s) * 32); \
;             o0 = __builtin_amdgcn_mfma_f32_32x32x16_bf16(a0_, pk, o0, 0, 0, 0); o1 = __builtin_amdgcn_mfma_f32_32x32x16_bf16(a1_, pk, o1, 0, 0, 0); } while (0)
; #define PVS(s, pk) do { const bf16x8 a0_ = *(const LAS bf16x8*)(vb + (s) * 32), a1_ = *(const LAS bf16x8*)(vb + 32 * VT_STRIDE + (s) * 32); \
;             o0 = __builtin_amdgcn_mfma_f32_32x32x16_bf16(a0_, pk, o0, 0, 0, 0); o1 = __builtin_amdgcn_mfma_f32_32x32x16_bf16(a1_, pk, o1, 0, 0, 0); } while (0)
; #define PVS(s, pk) do { const bf16x8 a0_ = *(const LAS bf16x8*)(vb + (s) * 32), a1_ = *(const LAS bf16x8*)(vb + 32 * VT_STRIDE + (s) * 32); \
;             o0 = __builtin_amdgcn_mfma_f32_32x32x16_bf16(a0_, pk, o0, 0, 0, 0); o1 = __builtin_amdgcn_mfma_f32_32x32x16_bf16(a1_, pk, o1, 0, 0, 0); } while (0)
; #define PVS(s, pk) do { const bf16x8 a0_ = *(const LAS bf16x8*)(vb + (s) * 32), a1_ = *(const LAS bf16x8*)(vb + 32 * VT_STRIDE + (s) * 32); \
;             o0 = __builtin_amdgcn_mfma_f32_32x32x16_bf16(a0_, pk, o0, 0, 0, 0); o1 = __builtin_amdgcn_mfma_f32_32x32x16_bf16(a1_, pk, o1, 0, 0, 0); } while (0)
; #define PVS(s, pk) do { const bf16x8 a0_ = *(const LAS bf16x8*)(vb + (s) * 32), a1_ = *(const LAS bf16x8*)(vb + 32 * VT_STRIDE + (s) * 32); \
;             o0 = __builtin_amdgcn_mfma_f32_32x32x16_bf16(a0_, pk, o0, 0, 0, 0); o1 = __builtin_amdgcn_mfma_f32_32x32x16_bf16(a1_, pk, o1, 0, 0, 0); } while (0)
; template <int MODE>
; __device__ __forceinline__ void attn_unit(LAS unsigned char* lds, const AttnArgs& A, int qb) {
;     ...
;         bool active;
;         if (MODE == M_XA) active = true;
;         else if (MODE == M_MOBA) active = (i < 4) ? (key0 <= w0 + 31) : (((wmask >> ((i - 4) >> 2)) & 1ull) != 0ull);
;         else active = key0 <= w0 + 31;
;     ...
;         } else {
;         if (prev_active) {
;             const LAS unsigned char* vb = lds + prevbuf + KB_BYTES + r32 * VT_STRIDE + hi * 16;
;     ...
;             PVS(0, pkP0); PVS(1, pkP1); PVS(2, pkP2); PVS(3, pkP3);
;     ...
;         }
;         }
;         prev_active = active; prevbuf = 0 * BUF_BYTES;
.LBB0_969:
	s_sub_i32 s80, s52, 63
	s_cmp_le_i32 s80, s48
	v_cndmask_b32_e64 v230, 0, 1, s[4:5]
	s_cselect_b64 s[26:27], -1, 0
	s_cmp_gt_i32 s80, s48
	s_mov_b64 s[28:29], -1
	v_cmp_ne_u32_e64 s[10:11], 1, v230
	s_cbranch_scc0 .LBB0_973
	s_and_b64 vcc, exec, s[10:11]
	s_cbranch_vccnz .LBB0_972
	v_add_u32_e32 v38, s2, v191
	ds_read_b128 v[234:237], v38 offset:8192
	ds_read_b128 v[34:37], v38 offset:12800
	s_waitcnt lgkmcnt(1)
	v_mfma_f32_32x32x16_bf16 v[2:17], v[234:237], v[150:153], v[2:17]
	s_waitcnt lgkmcnt(0)
	v_mfma_f32_32x32x16_bf16 v[18:33], v[34:37], v[150:153], v[18:33]
	ds_read_b128 v[34:37], v38 offset:8224
	s_waitcnt lgkmcnt(0)
	v_mfma_f32_32x32x16_bf16 v[2:17], v[34:37], v[142:145], v[2:17]
	ds_read_b128 v[34:37], v38 offset:12832
	s_waitcnt lgkmcnt(0)
	v_mfma_f32_32x32x16_bf16 v[18:33], v[34:37], v[142:145], v[18:33]
	ds_read_b128 v[34:37], v38 offset:8256
	s_waitcnt lgkmcnt(0)
	v_mfma_f32_32x32x16_bf16 v[2:17], v[34:37], v[146:149], v[2:17]
	ds_read_b128 v[34:37], v38 offset:12864
	s_waitcnt lgkmcnt(0)
	v_mfma_f32_32x32x16_bf16 v[18:33], v[34:37], v[146:149], v[18:33]
	ds_read_b128 v[34:37], v38 offset:8288
	s_waitcnt lgkmcnt(0)
	v_mfma_f32_32x32x16_bf16 v[2:17], v[34:37], v[138:141], v[2:17]
	ds_read_b128 v[34:37], v38 offset:12896
	s_waitcnt lgkmcnt(0)
	v_mfma_f32_32x32x16_bf16 v[18:33], v[34:37], v[138:141], v[18:33]

; #define LAS __attribute__((address_space(3)))
; template <int MODE>
; __device__ __forceinline__ void attn_unit(LAS unsigned char* lds, const AttnArgs& A, int qb) {
;     ...
;         if (active) {
;             f32x16 p0, p1;
; #pragma unroll
;             for (int r = 0; r < 16; ++r) { p0[r] = 0.f; p1[r] = 0.f; }
;             LAS unsigned char* kb = buf + kperm * 16 + hi * 1024;
; #pragma unroll
;             for (int d0 = 0; d0 < 4; ++d0) {
;                 const bf16x8 kf0 = *(const LAS bf16x8*)(kb + d0 * 2048), kf1 = *(const LAS bf16x8*)(kb + d0 * 2048 + 512);
;                 p0 = __builtin_amdgcn_mfma_f32_32x32x16_bf16(kf0, qr[d0], p0, 0, 0, 0);
;                 p1 = __builtin_amdgcn_mfma_f32_32x32x16_bf16(kf1, qr[d0], p1, 0, 0, 0);
;             }
;         if (prev_active) {
;             const LAS unsigned char* vb = lds + prevbuf + KB_BYTES + r32 * VT_STRIDE + hi * 16;
;     ...
;             PVS(0, pkP0); PVS(1, pkP1); PVS(2, pkP2); PVS(3, pkP3);
;     ...
;         }
;     ...
;                     if (MODE == M_FOX) {
;                         typedef float f32x2 __attribute__((ext_vector_type(2)));
;                         const float base = cq2 - fminf(qb2, 48.0f); const f32x2 basev = (f32x2){base, base}, c2v = (f32x2){C2, C2};
;                         f32x2 sa = (f32x2){0.f, 0.f}, sb = (f32x2){0.f, 0.f};
; #pragma unroll
;                         for (int r = 0; r < 16; r += 2) {
;                             const f32x2 ca = *(const LAS f32x2*)(cl + 16 * (r >> 3) + (r & 7)), cb = *(const LAS f32x2*)(cl + 32 + 16 * (r >> 3) + (r & 7));
;                             const f32x2 ta = (f32x2){p0[r], p0[r + 1]} * c2v + (basev - ca), tb = (f32x2){p1[r], p1[r + 1]} * c2v + (basev - cb);
;                             const f32x2 ea = (f32x2){__builtin_amdgcn_exp2f(ta.x), __builtin_amdgcn_exp2f(ta.y)}, eb = (f32x2){__builtin_amdgcn_exp2f(tb.x), __builtin_amdgcn_exp2f(tb.y)};
;                             sa += ea; sb += eb; p0[r] = ea.x; p0[r + 1] = ea.y; p1[r] = eb.x; p1[r + 1] = eb.y;
;                         }
;                         corr = 1.0f; l_run += (sa.x + sa.y) + (sb.x + sb.y);
.LBB0_973:
	s_andn2_b64 vcc, exec, s[28:29]
	s_cbranch_vccnz .LBB0_981
	s_nop 5
	v_add_u32_e32 v238, v186, v187
	ds_read_b128 v[230:233], v238
	s_and_b64 vcc, exec, s[10:11]
	s_waitcnt lgkmcnt(0)
	v_mfma_f32_32x32x16_bf16 v[34:49], v[230:233], v[98:101], 0
	ds_read_b128 v[230:233], v238 offset:512
	s_waitcnt lgkmcnt(0)
	v_mfma_f32_32x32x16_bf16 v[50:65], v[230:233], v[98:101], 0
	ds_read_b128 v[230:233], v238 offset:2048
	s_waitcnt lgkmcnt(0)
	v_mfma_f32_32x32x16_bf16 v[34:49], v[230:233], v[102:105], v[34:49]
	ds_read_b128 v[230:233], v238 offset:2560
	s_waitcnt lgkmcnt(0)
	v_mfma_f32_32x32x16_bf16 v[50:65], v[230:233], v[102:105], v[50:65]
	ds_read_b128 v[230:233], v238 offset:4096
	s_waitcnt lgkmcnt(0)
	v_mfma_f32_32x32x16_bf16 v[34:49], v[230:233], v[106:109], v[34:49]
	ds_read_b128 v[230:233], v238 offset:4608
	s_waitcnt lgkmcnt(0)
	v_mfma_f32_32x32x16_bf16 v[50:65], v[230:233], v[106:109], v[50:65]
	ds_read_b128 v[230:233], v238 offset:6144
	s_waitcnt lgkmcnt(0)
	v_mfma_f32_32x32x16_bf16 v[34:49], v[230:233], v[110:113], v[34:49]
	ds_read_b128 v[230:233], v238 offset:6656
	s_waitcnt lgkmcnt(0)
	v_mfma_f32_32x32x16_bf16 v[50:65], v[230:233], v[110:113], v[50:65]
	s_cbranch_vccnz .LBB0_976
	v_add_u32_e32 v238, s2, v191
	ds_read_b128 v[230:233], v238 offset:8192
	s_waitcnt lgkmcnt(0)
	v_mfma_f32_32x32x16_bf16 v[2:17], v[230:233], v[150:153], v[2:17]
	ds_read_b128 v[230:233], v238 offset:12800
	s_waitcnt lgkmcnt(0)
	v_mfma_f32_32x32x16_bf16 v[18:33], v[230:233], v[150:153], v[18:33]
	ds_read_b128 v[230:233], v238 offset:8224
	s_waitcnt lgkmcnt(0)
	v_mfma_f32_32x32x16_bf16 v[2:17], v[230:233], v[142:145], v[2:17]
	ds_read_b128 v[230:233], v238 offset:12832
	s_waitcnt lgkmcnt(0)
	v_mfma_f32_32x32x16_bf16 v[18:33], v[230:233], v[142:145], v[18:33]
	ds_read_b128 v[230:233], v238 offset:8256
	s_waitcnt lgkmcnt(0)
	v_mfma_f32_32x32x16_bf16 v[2:17], v[230:233], v[146:149], v[2:17]
	ds_read_b128 v[230:233], v238 offset:12864
	s_waitcnt lgkmcnt(0)
	v_mfma_f32_32x32x16_bf16 v[18:33], v[230:233], v[146:149], v[18:33]
	ds_read_b128 v[230:233], v238 offset:12896
	s_waitcnt lgkmcnt(0)
	v_mfma_f32_32x32x16_bf16 v[18:33], v[230:233], v[138:141], v[18:33]
	ds_read_b128 v[230:233], v238 offset:8288
	s_waitcnt lgkmcnt(0)
	v_mfma_f32_32x32x16_bf16 v[2:17], v[230:233], v[138:141], v[2:17]
.LBB0_976:
	s_nop 8
	s_nop 3
	s_cmp_gt_i32 s52, s43
	s_mov_b64 s[4:5], -1
	s_cbranch_scc1 .LBB0_978
	ds_read_b128 v[66:69], v188 offset:17408
	ds_read_b128 v[70:73], v188 offset:17424
	ds_read_b128 v[74:77], v188 offset:17536
	s_mov_b64 s[4:5], 0
	s_waitcnt lgkmcnt(2)
	v_pk_add_f32 v[66:67], v[160:161], v[66:67] neg_lo:[0,1] neg_hi:[0,1]
	s_nop 0
	v_pk_fma_f32 v[66:67], v[34:35], s[78:79], v[66:67] op_sel_hi:[1,0,1]
	v_pk_add_f32 v[68:69], v[160:161], v[68:69] neg_lo:[0,1] neg_hi:[0,1]
	v_exp_f32_e32 v82, v66
	v_exp_f32_e32 v83, v67
	v_pk_fma_f32 v[68:69], v[36:37], s[78:79], v[68:69] op_sel_hi:[1,0,1]
	s_waitcnt lgkmcnt(0)
	v_pk_add_f32 v[74:75], v[160:161], v[74:75] neg_lo:[0,1] neg_hi:[0,1]
	v_exp_f32_e32 v84, v68
	v_exp_f32_e32 v85, v69
	v_pk_fma_f32 v[74:75], v[50:51], s[78:79], v[74:75] op_sel_hi:[1,0,1]
	v_pk_add_f32 v[76:77], v[160:161], v[76:77] neg_lo:[0,1] neg_hi:[0,1]
	v_exp_f32_e32 v66, v74
	v_exp_f32_e32 v67, v75
	v_pk_add_f32 v[74:75], v[82:83], 0 op_sel_hi:[1,0]
	v_pk_fma_f32 v[76:77], v[52:53], s[78:79], v[76:77] op_sel_hi:[1,0,1]
	v_pk_add_f32 v[80:81], v[74:75], v[84:85]
	v_exp_f32_e32 v68, v76
	v_exp_f32_e32 v69, v77
	ds_read_b128 v[74:77], v188 offset:17552
	v_pk_add_f32 v[70:71], v[160:161], v[70:71] neg_lo:[0,1] neg_hi:[0,1]
	v_pk_add_f32 v[72:73], v[160:161], v[72:73] neg_lo:[0,1] neg_hi:[0,1]
	v_pk_fma_f32 v[70:71], v[38:39], s[78:79], v[70:71] op_sel_hi:[1,0,1]
	v_pk_fma_f32 v[72:73], v[40:41], s[78:79], v[72:73] op_sel_hi:[1,0,1]
	s_waitcnt lgkmcnt(0)
	v_pk_add_f32 v[74:75], v[160:161], v[74:75] neg_lo:[0,1] neg_hi:[0,1]
	v_pk_add_f32 v[76:77], v[160:161], v[76:77] neg_lo:[0,1] neg_hi:[0,1]
	v_pk_fma_f32 v[74:75], v[54:55], s[78:79], v[74:75] op_sel_hi:[1,0,1]
	v_exp_f32_e32 v86, v70
	v_exp_f32_e32 v87, v71
	v_exp_f32_e32 v70, v74
	v_exp_f32_e32 v71, v75
	v_pk_fma_f32 v[76:77], v[56:57], s[78:79], v[76:77] op_sel_hi:[1,0,1]
	v_exp_f32_e32 v88, v72
	v_exp_f32_e32 v89, v73
	v_exp_f32_e32 v72, v76
	v_exp_f32_e32 v73, v77
	v_pk_add_f32 v[78:79], v[66:67], 0 op_sel_hi:[1,0]
	v_pk_add_f32 v[74:75], v[80:81], v[86:87]
	v_pk_add_f32 v[78:79], v[78:79], v[68:69]
	v_pk_add_f32 v[92:93], v[74:75], v[88:89]
	v_pk_add_f32 v[78:79], v[78:79], v[70:71]
	s_nop 0
	v_pk_add_f32 v[94:95], v[78:79], v[72:73]
	ds_read_b128 v[74:77], v188 offset:17472
	ds_read_b128 v[78:81], v188 offset:17600
	s_waitcnt lgkmcnt(1)
	v_pk_add_f32 v[74:75], v[160:161], v[74:75] neg_lo:[0,1] neg_hi:[0,1]
	s_nop 0
	v_pk_fma_f32 v[74:75], v[42:43], s[78:79], v[74:75] op_sel_hi:[1,0,1]
	s_waitcnt lgkmcnt(0)
	v_pk_add_f32 v[78:79], v[160:161], v[78:79] neg_lo:[0,1] neg_hi:[0,1]
	v_exp_f32_e32 v90, v74
	v_exp_f32_e32 v91, v75
	v_pk_fma_f32 v[78:79], v[58:59], s[78:79], v[78:79] op_sel_hi:[1,0,1]
	v_pk_add_f32 v[76:77], v[160:161], v[76:77] neg_lo:[0,1] neg_hi:[0,1]
	v_pk_add_f32 v[80:81], v[160:161], v[80:81] neg_lo:[0,1] neg_hi:[0,1]
	v_exp_f32_e32 v74, v78
	v_exp_f32_e32 v75, v79
	v_pk_fma_f32 v[76:77], v[44:45], s[78:79], v[76:77] op_sel_hi:[1,0,1]
	v_pk_fma_f32 v[80:81], v[60:61], s[78:79], v[80:81] op_sel_hi:[1,0,1]
	v_pk_add_f32 v[78:79], v[92:93], v[90:91]
	v_exp_f32_e32 v92, v76
	v_exp_f32_e32 v93, v77
	v_exp_f32_e32 v76, v80
	v_exp_f32_e32 v77, v81
	v_pk_add_f32 v[94:95], v[94:95], v[74:75]
	v_pk_add_f32 v[138:139], v[78:79], v[92:93]
	v_pk_add_f32 v[140:141], v[94:95], v[76:77]
	ds_read_b128 v[78:81], v188 offset:17488
	ds_read_b128 v[94:97], v188 offset:17616
	s_waitcnt lgkmcnt(1)
	v_pk_add_f32 v[78:79], v[160:161], v[78:79] neg_lo:[0,1] neg_hi:[0,1]
	s_waitcnt lgkmcnt(0)
	v_pk_add_f32 v[94:95], v[160:161], v[94:95] neg_lo:[0,1] neg_hi:[0,1]
	v_pk_fma_f32 v[78:79], v[46:47], s[78:79], v[78:79] op_sel_hi:[1,0,1]
	v_pk_fma_f32 v[142:143], v[62:63], s[78:79], v[94:95] op_sel_hi:[1,0,1]
	v_pk_add_f32 v[80:81], v[160:161], v[80:81] neg_lo:[0,1] neg_hi:[0,1]
	v_pk_add_f32 v[96:97], v[160:161], v[96:97] neg_lo:[0,1] neg_hi:[0,1]
	v_exp_f32_e32 v94, v78
	v_exp_f32_e32 v95, v79
	v_exp_f32_e32 v78, v142
	v_exp_f32_e32 v79, v143
	v_pk_fma_f32 v[80:81], v[48:49], s[78:79], v[80:81] op_sel_hi:[1,0,1]
	v_pk_fma_f32 v[142:143], v[64:65], s[78:79], v[96:97] op_sel_hi:[1,0,1]
	v_exp_f32_e32 v96, v80
	v_exp_f32_e32 v97, v81
	v_exp_f32_e32 v80, v142
	v_exp_f32_e32 v81, v143
	v_pk_add_f32 v[138:139], v[138:139], v[94:95]
	v_pk_add_f32 v[140:141], v[140:141], v[78:79]
	v_pk_add_f32 v[138:139], v[138:139], v[96:97]
	v_pk_add_f32 v[140:141], v[140:141], v[80:81]
	v_mov_b32_e32 v142, v138
	v_mov_b32_e32 v143, v140
	v_mov_b32_e32 v140, v139
	v_pk_add_f32 v[138:139], v[142:143], v[140:141]
	s_nop 0
	v_add_f32_e32 v138, v138, v139

; #define LAS __attribute__((address_space(3)))
; #define PVS(s, pk) do { const bf16x8 a0_ = *(const LAS bf16x8*)(vb + (s) * 32), a1_ = *(const LAS bf16x8*)(vb + 32 * VT_STRIDE + (s) * 32); \
;             o0 = __builtin_amdgcn_mfma_f32_32x32x16_bf16(a0_, pk, o0, 0, 0, 0); o1 = __builtin_amdgcn_mfma_f32_32x32x16_bf16(a1_, pk, o1, 0, 0, 0); } while (0)
; #define PVS(s, pk) do { const bf16x8 a0_ = *(const LAS bf16x8*)(vb + (s) * 32), a1_ = *(const LAS bf16x8*)(vb + 32 * VT_STRIDE + (s) * 32); \
;             o0 = __builtin_amdgcn_mfma_f32_32x32x16_bf16(a0_, pk, o0, 0, 0, 0); o1 = __builtin_amdgcn_mfma_f32_32x32x16_bf16(a1_, pk, o1, 0, 0, 0); } while (0)
; #define PVS(s, pk) do { const bf16x8 a0_ = *(const LAS bf16x8*)(vb + (s) * 32), a1_ = *(const LAS bf16x8*)(vb + 32 * VT_STRIDE + (s) * 32); \
;             o0 = __builtin_amdgcn_mfma_f32_32x32x16_bf16(a0_, pk, o0, 0, 0, 0); o1 = __builtin_amdgcn_mfma_f32_32x32x16_bf16(a1_, pk, o1, 0, 0, 0); } while (0)
; #define PVS(s, pk) do { const bf16x8 a0_ = *(const LAS bf16x8*)(vb + (s) * 32), a1_ = *(const LAS bf16x8*)(vb + 32 * VT_STRIDE + (s) * 32); \
;             o0 = __builtin_amdgcn_mfma_f32_32x32x16_bf16(a0_, pk, o0, 0, 0, 0); o1 = __builtin_amdgcn_mfma_f32_32x32x16_bf16(a1_, pk, o1, 0, 0, 0); } while (0)
; #define PVS(s, pk) do { const bf16x8 a0_ = *(const LAS bf16x8*)(vb + (s) * 32), a1_ = *(const LAS bf16x8*)(vb + 32 * VT_STRIDE + (s) * 32); \
;             o0 = __builtin_amdgcn_mfma_f32_32x32x16_bf16(a0_, pk, o0, 0, 0, 0); o1 = __builtin_amdgcn_mfma_f32_32x32x16_bf16(a1_, pk, o1, 0, 0, 0); } while (0)
; #define PVS(s, pk) do { const bf16x8 a0_ = *(const LAS bf16x8*)(vb + (s) * 32), a1_ = *(const LAS bf16x8*)(vb + 32 * VT_STRIDE + (s) * 32); \
;             o0 = __builtin_amdgcn_mfma_f32_32x32x16_bf16(a0_, pk, o0, 0, 0, 0); o1 = __builtin_amdgcn_mfma_f32_32x32x16_bf16(a1_, pk, o1, 0, 0, 0); } while (0)
; template <int MODE>
; __device__ __forceinline__ void attn_unit(LAS unsigned char* lds, const AttnArgs& A, int qb) {
;     ...
;         }
;     }
;     ...
;     if (prev_active) {
;         const LAS unsigned char* vb = lds + prevbuf + KB_BYTES + r32 * VT_STRIDE + hi * 16;
;     ...
;         PVS(0, pkP0); PVS(1, pkP1); PVS(2, pkP2); PVS(3, pkP3);
;     ...
;     }
.LBB0_1046:
	s_mov_b64 s[4:5], s[26:27]
	s_and_b64 vcc, exec, s[10:11]
	s_cbranch_vccz .LBB0_964
.Lfox_exit_o:
	v_mov_b64_e32 v[96:97], v[16:17]
	v_mov_b64_e32 v[80:81], v[32:33]
	v_mov_b64_e32 v[94:95], v[14:15]
	v_mov_b64_e32 v[92:93], v[12:13]
	v_mov_b64_e32 v[90:91], v[10:11]
	v_mov_b64_e32 v[88:89], v[8:9]
	v_mov_b64_e32 v[86:87], v[6:7]
	v_mov_b64_e32 v[84:85], v[4:5]
	v_mov_b64_e32 v[82:83], v[2:3]
	v_mov_b64_e32 v[78:79], v[30:31]
	v_mov_b64_e32 v[76:77], v[28:29]
	v_mov_b64_e32 v[74:75], v[26:27]
	v_mov_b64_e32 v[72:73], v[24:25]
	v_mov_b64_e32 v[70:71], v[22:23]
	v_mov_b64_e32 v[68:69], v[20:21]
	v_mov_b64_e32 v[66:67], v[18:19]
.LBB0_1047:
	s_waitcnt vmcnt(0)
	s_andn2_b64 vcc, exec, s[4:5]
	s_cbranch_vccnz .LBB0_943
	s_add_i32 s0, s2, 0
	v_add3_u32 v0, s0, v185, v0
	ds_read_b128 v[2:5], v0 offset:8192
	s_waitcnt lgkmcnt(0)
	v_mfma_f32_32x32x16_bf16 v[82:97], v[2:5], v[150:153], v[82:97]
	ds_read_b128 v[2:5], v0 offset:12800
	s_waitcnt lgkmcnt(0)
	v_mfma_f32_32x32x16_bf16 v[66:81], v[2:5], v[150:153], v[66:81]
	ds_read_b128 v[2:5], v0 offset:8224
	s_waitcnt lgkmcnt(0)
	v_mfma_f32_32x32x16_bf16 v[82:97], v[2:5], v[142:145], v[82:97]
	ds_read_b128 v[2:5], v0 offset:12832
	s_waitcnt lgkmcnt(0)
	v_mfma_f32_32x32x16_bf16 v[66:81], v[2:5], v[142:145], v[66:81]
	ds_read_b128 v[2:5], v0 offset:8256
	s_waitcnt lgkmcnt(0)
	v_mfma_f32_32x32x16_bf16 v[82:97], v[2:5], v[146:149], v[82:97]
	ds_read_b128 v[2:5], v0 offset:12864
	s_waitcnt lgkmcnt(0)
	v_mfma_f32_32x32x16_bf16 v[66:81], v[2:5], v[146:149], v[66:81]
	ds_read_b128 v[2:5], v0 offset:8288
	s_waitcnt lgkmcnt(0)
	v_mfma_f32_32x32x16_bf16 v[82:97], v[2:5], v[138:141], v[82:97]
	ds_read_b128 v[2:5], v0 offset:12896
	s_waitcnt lgkmcnt(0)
	v_mfma_f32_32x32x16_bf16 v[66:81], v[2:5], v[138:141], v[66:81]
	s_branch .LBB0_943
